# v082 + first V fragment group requested behind the 4th QK MFMA (into the registers the first K fragments free), second group behind the 8th
# speedup vs baseline: 1.0037x; 1.0037x over previous
; #define ALAS __attribute__((address_space(3)))
; template <bool WIN> ...
;     ...
;         if (tr + 3 < NT) AT_DMA(tr + 3);
;         const int k0 = (t_lo + tr) * 64;
;         const bool skip = WIN && (k0 > qw + 31 + 128 || k0 + 63 < qw - 128);
;         if (!skip) {
;             const bool near = WIN || ((k0 - (qw + 31)) < 128 && (qw - (k0 + 63)) < 128);
;             const float cinit = near ? 0.f : (k0 > qw ? cfar_hi : cfar_lo);
;             if (__builtin_expect(cinit != cbase, 0)) { cbase = cinit; asm volatile("" ::: "memory");
; #pragma unroll
;                 for (int r = 0; r < 16; ++r) cvec[r] = cbase - m_ref; }
;             f32x16 s0, s1;
;             const ALAS unsigned char* sb = lds + (tr & (NSTG - 1)) * STAGE;
;             {
;                 bf16x8 ka[8];
; #pragma unroll
;                 for (int ds = 0; ds < 4; ++ds) { ka[2 * ds] = *(const ALAS bf16x8*)(sb + kx[ds]); ka[2 * ds + 1] = *(const ALAS bf16x8*)(sb + kx[ds] + 4096); }
;                 __builtin_amdgcn_sched_barrier(0);
;                 s0 = __builtin_amdgcn_mfma_f32_32x32x16_bf16(ka[0], qf(0), cvec, 0, 0, 0);
;                 s1 = __builtin_amdgcn_mfma_f32_32x32x16_bf16(ka[1], qf(0), cvec, 0, 0, 0);
; #pragma unroll
;                 for (int ds = 1; ds < 4; ++ds) {
;                     s0 = __builtin_amdgcn_mfma_f32_32x32x16_bf16(ka[2 * ds], qf(ds), s0, 0, 0, 0);
;                     s1 = __builtin_amdgcn_mfma_f32_32x32x16_bf16(ka[2 * ds + 1], qf(ds), s1, 0, 0, 0);
;                 }
;             }
;             bf16x8 va[2 * NDB], vc[2 * NDB];
; #pragma unroll
;             for (int kk = 0; kk < 2; ++kk)
; #pragma unroll
;                 for (int db = 0; db < NDB; ++db) va[kk * NDB + db] = *(const ALAS bf16x8*)(sb + vx[kk] + db * 4096);
;             __builtin_amdgcn_sched_barrier(0);
;             if (near) {
;                 const ALAS float* lb = lut + (k0 + 8 * hi - qabs + LUTC);
; #pragma unroll
;                 for (int r = 0; r < 16; ++r) { s0[r] += lb[16 * (r >> 3) + (r & 7)]; s1[r] += lb[32 + 16 * (r >> 3) + (r & 7)];
;                     if ((r & 7) == 7) __builtin_amdgcn_sched_barrier(0); }
;             }
.LSPp_k0bk:
	s_mov_b32 m0, s98
	v_mfma_f32_32x32x16_bf16 v[98:113], v[130:133], v[126:129], v[66:81]
	global_load_lds_dwordx4 v[174:175], off
	s_add_i32 m0, s98, 0x2000
	v_mfma_f32_32x32x16_bf16 v[82:97], v[134:137], v[126:129], v[66:81]
	global_load_lds_dwordx4 v[208:209], off
	s_add_i32 m0, s101, 0x4000
	v_mfma_f32_32x32x16_bf16 v[98:113], v[138:141], v[122:125], v[98:113]
	global_load_lds_dwordx4 v[172:173], off
	s_add_i32 m0, s101, 0x6000
	v_mfma_f32_32x32x16_bf16 v[82:97], v[142:145], v[122:125], v[82:97]
	global_load_lds_dwordx4 v[210:211], off
	v_add3_u32 v236, s99, v179, v187
	ds_read_b128 v[130:133], v236 offset:16384
	ds_read_b128 v[134:137], v236 offset:20480
	ds_read_b128 v[138:141], v236 offset:24576
	ds_read_b128 v[142:145], v236 offset:28672
	v_mfma_f32_32x32x16_bf16 v[98:113], v[146:149], v[118:121], v[98:113]
	v_mfma_f32_32x32x16_bf16 v[82:97], v[150:153], v[118:121], v[82:97]
	v_mfma_f32_32x32x16_bf16 v[98:113], v[158:161], v[114:117], v[98:113]
	v_mfma_f32_32x32x16_bf16 v[82:97], v[204:207], v[114:117], v[82:97]
	v_add3_u32 v237, s99, v181, v187
	ds_read_b128 v[146:149], v237 offset:16384
	ds_read_b128 v[150:153], v237 offset:20480
	ds_read_b128 v[154:157], v237 offset:24576
	ds_read_b128 v[158:161], v237 offset:28672
	s_nop 0
	s_branch .LSPp_vrd2
.LSPp_vrd:
	v_add3_u32 v236, s99, v179, v187
	ds_read_b128 v[130:133], v236 offset:16384
	ds_read_b128 v[134:137], v236 offset:20480
	ds_read_b128 v[138:141], v236 offset:24576
	ds_read_b128 v[142:145], v236 offset:28672
	v_add3_u32 v237, s99, v181, v187
	ds_read_b128 v[146:149], v237 offset:16384
	ds_read_b128 v[150:153], v237 offset:20480
	ds_read_b128 v[154:157], v237 offset:24576
	ds_read_b128 v[158:161], v237 offset:28672
.LSPp_vrd2:
	s_cmp_eq_u32 s64, 0
	s_cbranch_scc1 .LSPp_pv
	v_add_u32_e32 v203, s84, v171
	v_add_u32_e32 v204, 0x23b80, v203
	v_add_u32_e32 v206, 0x23c00, v203
	v_add_u32_e32 v210, 0x23c08, v203
	v_add_u32_e32 v208, 0x23b88, v203
	v_add_u32_e32 v218, 0x23c10, v203
	v_add_u32_e32 v212, 0x23b90, v203
	v_add_u32_e32 v216, 0x23c18, v203
	v_add_u32_e32 v214, 0x23b98, v203
	ds_read2_b32 v[204:205], v204 offset1:1
	ds_read2_b32 v[206:207], v206 offset1:1
	ds_read2_b32 v[208:209], v208 offset1:1
	ds_read2_b32 v[210:211], v210 offset1:1
	ds_read2_b32 v[212:213], v212 offset1:1
	ds_read2_b32 v[214:215], v214 offset1:1
	ds_read2_b32 v[216:217], v216 offset1:1
	ds_read2_b32 v[218:219], v218 offset1:1
	v_add_u32_e32 v220, 0x23bc0, v203
	v_add_u32_e32 v222, 0x23c40, v203
	v_add_u32_e32 v226, 0x23c48, v203
	v_add_u32_e32 v224, 0x23bc8, v203
	v_add_u32_e32 v228, 0x23bd0, v203
	v_add_u32_e32 v234, 0x23c58, v203
	ds_read2_b32 v[220:221], v220 offset1:1
	ds_read2_b32 v[222:223], v222 offset1:1
	ds_read2_b32 v[224:225], v224 offset1:1
	ds_read2_b32 v[226:227], v226 offset1:1
	v_add_u32_e32 v231, 0x23c50, v203
	v_add_u32_e32 v203, 0x23bd8, v203
	ds_read2_b32 v[228:229], v228 offset1:1
	ds_read2_b32 v[232:233], v203 offset1:1
	ds_read2_b32 v[234:235], v234 offset1:1
	ds_read2_b32 v[236:237], v231 offset1:1
	s_waitcnt lgkmcnt(10)
	v_pk_add_f32 v[104:105], v[104:105], v[214:215]
	v_pk_add_f32 v[102:103], v[102:103], v[212:213]
	v_pk_add_f32 v[100:101], v[100:101], v[208:209]
	s_waitcnt lgkmcnt(2)
	v_pk_add_f32 v[112:113], v[112:113], v[232:233]
	v_pk_add_f32 v[110:111], v[110:111], v[228:229]
	v_pk_add_f32 v[108:109], v[108:109], v[224:225]
	v_pk_add_f32 v[106:107], v[106:107], v[220:221]
	v_pk_add_f32 v[98:99], v[98:99], v[204:205]
	v_pk_add_f32 v[88:89], v[88:89], v[216:217]
	v_pk_add_f32 v[86:87], v[86:87], v[218:219]
	v_pk_add_f32 v[84:85], v[84:85], v[210:211]
	s_waitcnt lgkmcnt(1)
	v_pk_add_f32 v[96:97], v[96:97], v[234:235]
	s_waitcnt lgkmcnt(0)
	v_pk_add_f32 v[94:95], v[94:95], v[236:237]
	v_pk_add_f32 v[92:93], v[92:93], v[226:227]
	v_pk_add_f32 v[90:91], v[90:91], v[222:223]
	v_pk_add_f32 v[82:83], v[82:83], v[206:207]
; #define ALAS __attribute__((address_space(3)))
; template <bool WIN> ...
;     ...
;             float ls0 = 0.f, ls1 = 0.f;
;     ...
;             union PFU { u32x4 u; bf16x8 b; };
;             PFU p0, p1, p2, p3;
;             AT_EXP(s0, 0, p0);
; #pragma unroll
;             for (int kk = 0; kk < 2; ++kk)
; #pragma unroll
;                 for (int db = 0; db < NDB; ++db) vc[kk * NDB + db] = *(const ALAS bf16x8*)(sb + vx[kk + 2] + db * 4096);
;             __builtin_amdgcn_sched_barrier(0);
; #pragma unroll
;             for (int db = 0; db < NDB; ++db) o[db] = __builtin_amdgcn_mfma_f32_32x32x16_bf16(va[db], p0.b, o[db], 0, 0, 0);
;             AT_EXP(s0, 8, p1);
;             __builtin_amdgcn_sched_barrier(0);
; #pragma unroll
;             for (int db = 0; db < NDB; ++db) o[db] = __builtin_amdgcn_mfma_f32_32x32x16_bf16(va[NDB + db], p1.b, o[db], 0, 0, 0);
;             AT_EXP(s1, 0, p2);
;             __builtin_amdgcn_sched_barrier(0);
; #pragma unroll
;             for (int db = 0; db < NDB; ++db) o[db] = __builtin_amdgcn_mfma_f32_32x32x16_bf16(vc[db], p2.b, o[db], 0, 0, 0);
;             AT_EXP(s1, 8, p3);
;             __builtin_amdgcn_sched_barrier(0);
; #pragma unroll
;             for (int db = 0; db < NDB; ++db) o[db] = __builtin_amdgcn_mfma_f32_32x32x16_bf16(vc[NDB + db], p3.b, o[db], 0, 0, 0);
;             __builtin_amdgcn_sched_barrier(0);
;     ...
;             l_run += ls0 + ls1;
.LSPp_pv:
	s_cmp_eq_u32 s86, 0
	s_cbranch_scc1 .LSPp_pure
	s_waitcnt lgkmcnt(4)
	v_mfma_f32_32x32x16_bf16 v[50:65], v[130:133], v[238:241], v[50:65]
	v_exp_f32_e32 v98, v98
	v_exp_f32_e32 v99, v99
	v_mfma_f32_32x32x16_bf16 v[34:49], v[134:137], v[238:241], v[34:49]
	v_exp_f32_e32 v100, v100
	v_exp_f32_e32 v101, v101
	v_mfma_f32_32x32x16_bf16 v[18:33], v[138:141], v[238:241], v[18:33]
	v_exp_f32_e32 v102, v102
	v_exp_f32_e32 v103, v103
	v_add_f32_e32 v228, v98, v100
	v_add_f32_e32 v229, v99, v101
	v_mfma_f32_32x32x16_bf16 v[2:17], v[142:145], v[238:241], v[2:17]
	v_exp_f32_e32 v104, v104
	v_exp_f32_e32 v105, v105
	v_add_f32_e32 v228, v228, v102
	v_add_f32_e32 v229, v229, v103
	v_add3_u32 v236, s99, v183, v187
	ds_read_b128 v[130:133], v236 offset:16384
	ds_read_b128 v[134:137], v236 offset:20480
	ds_read_b128 v[138:141], v236 offset:24576
	ds_read_b128 v[142:145], v236 offset:28672
	s_waitcnt lgkmcnt(4)
	v_mfma_f32_32x32x16_bf16 v[50:65], v[146:149], v[242:245], v[50:65]
	v_exp_f32_e32 v106, v106
	v_exp_f32_e32 v107, v107
	v_add_f32_e32 v228, v228, v104
	v_add_f32_e32 v229, v229, v105
	v_cvt_pk_bf16_f32 v238, v98, v99
	v_lshl_add_u64 v[174:175], v[174:175], 0, s[60:61]
	s_add_i32 s87, s85, 0xffff8000
	s_and_b32 s87, s87, 0x18000
	v_mfma_f32_32x32x16_bf16 v[34:49], v[150:153], v[242:245], v[34:49]
	v_exp_f32_e32 v108, v108
	v_exp_f32_e32 v109, v109
	v_add_f32_e32 v228, v228, v106
	v_add_f32_e32 v229, v229, v107
	v_cvt_pk_bf16_f32 v239, v100, v101
	v_lshl_add_u64 v[172:173], v[172:173], 0, s[48:49]
	s_add_i32 s98, s85, 0x10000
	s_and_b32 s98, s98, 0x18000
	v_mfma_f32_32x32x16_bf16 v[18:33], v[154:157], v[242:245], v[18:33]
	v_exp_f32_e32 v110, v110
	v_exp_f32_e32 v111, v111
	v_add_f32_e32 v228, v228, v108
	v_add_f32_e32 v229, v229, v109
	v_cvt_pk_bf16_f32 v240, v102, v103
	v_lshl_add_u64 v[208:209], v[174:175], 0, s[40:41]
	s_add_i32 s98, s98, s20
	s_add_i32 s101, s85, 0x8000
	v_mfma_f32_32x32x16_bf16 v[2:17], v[158:161], v[242:245], v[2:17]
	v_exp_f32_e32 v112, v112
	v_exp_f32_e32 v113, v113
	v_add_f32_e32 v228, v228, v110
	v_add_f32_e32 v229, v229, v111
	v_cvt_pk_bf16_f32 v241, v104, v105
	v_lshl_add_u64 v[210:211], v[172:173], 0, s[40:41]
	s_and_b32 s101, s101, 0x18000
	s_add_i32 s101, s101, s20
	v_add3_u32 v237, s99, v190, v187
	ds_read_b128 v[146:149], v237 offset:16384
	ds_read_b128 v[150:153], v237 offset:20480
	ds_read_b128 v[154:157], v237 offset:24576
	ds_read_b128 v[158:161], v237 offset:28672
	s_waitcnt lgkmcnt(4)
	v_mfma_f32_32x32x16_bf16 v[50:65], v[130:133], v[246:249], v[50:65]
	v_exp_f32_e32 v82, v82
	v_exp_f32_e32 v83, v83
	v_add_f32_e32 v228, v228, v112
	v_add_f32_e32 v229, v229, v113
	v_cvt_pk_bf16_f32 v242, v106, v107
	v_add3_u32 v212, s87, v178, v162
	s_add_i32 s99, s81, s83
	s_add_i32 s99, s99, 64
	v_mfma_f32_32x32x16_bf16 v[34:49], v[134:137], v[246:249], v[34:49]
	v_exp_f32_e32 v84, v84
	v_exp_f32_e32 v85, v85
	v_add_f32_e32 v228, v228, v82
	v_add_f32_e32 v229, v229, v83
	v_cvt_pk_bf16_f32 v243, v108, v109
	v_add3_u32 v213, s87, v180, v162
	s_sub_i32 m0, s82, 64
	s_max_i32 s99, s99, m0
	v_mfma_f32_32x32x16_bf16 v[18:33], v[138:141], v[246:249], v[18:33]
	v_exp_f32_e32 v86, v86
	v_exp_f32_e32 v87, v87
	v_add_f32_e32 v228, v228, v84
	v_add_f32_e32 v229, v229, v85
	v_cvt_pk_bf16_f32 v244, v110, v111
	v_add3_u32 v214, s87, v182, v162
	s_add_i32 m0, s83, 64
	s_cmp_gt_i32 m0, s78
	v_mfma_f32_32x32x16_bf16 v[2:17], v[142:145], v[246:249], v[2:17]
	v_exp_f32_e32 v88, v88
	v_exp_f32_e32 v89, v89
	v_add_f32_e32 v228, v228, v86
	v_add_f32_e32 v229, v229, v87
	v_cvt_pk_bf16_f32 v245, v112, v113
	v_add3_u32 v215, s87, v184, v162
	s_cselect_b32 m0, s80, s79
	s_cmpk_lt_i32 s99, 0x80
	s_waitcnt lgkmcnt(0)
	v_mfma_f32_32x32x16_bf16 v[50:65], v[146:149], v[250:253], v[50:65]
	v_exp_f32_e32 v90, v90
	v_exp_f32_e32 v91, v91
	v_add_f32_e32 v228, v228, v88
	v_add_f32_e32 v229, v229, v89
	v_cvt_pk_bf16_f32 v246, v82, v83
	s_cselect_b32 s65, 1, 0
	s_cselect_b32 m0, 0, m0
	v_mfma_f32_32x32x16_bf16 v[34:49], v[150:153], v[250:253], v[34:49]
	v_exp_f32_e32 v92, v92
	v_exp_f32_e32 v93, v93
	v_add_f32_e32 v228, v228, v90
	v_add_f32_e32 v229, v229, v91
	v_cvt_pk_bf16_f32 v247, v84, v85
	s_add_i32 s99, s85, 0xffff0000
	s_and_b32 s99, s99, 0x18000
	v_mfma_f32_32x32x16_bf16 v[18:33], v[154:157], v[250:253], v[18:33]
	v_exp_f32_e32 v94, v94
	v_exp_f32_e32 v95, v95
	v_add_f32_e32 v228, v228, v92
	v_add_f32_e32 v229, v229, v93
	v_cvt_pk_bf16_f32 v248, v86, v87
	v_mfma_f32_32x32x16_bf16 v[2:17], v[158:161], v[250:253], v[2:17]
	v_exp_f32_e32 v96, v96
	v_exp_f32_e32 v97, v97
	v_add_f32_e32 v228, v228, v94
	v_add_f32_e32 v229, v229, v95
	v_cvt_pk_bf16_f32 v249, v88, v89
	v_add_f32_e32 v228, v228, v96
	v_add_f32_e32 v229, v229, v97
	v_cvt_pk_bf16_f32 v250, v90, v91
	v_cvt_pk_bf16_f32 v251, v92, v93
	v_cvt_pk_bf16_f32 v252, v94, v95
	v_cvt_pk_bf16_f32 v253, v96, v97
	ds_read_b128 v[130:133], v212
	ds_read_b128 v[134:137], v212 offset:4096
	ds_read_b128 v[138:141], v213
	ds_read_b128 v[142:145], v213 offset:4096
	ds_read_b128 v[146:149], v214
	ds_read_b128 v[150:153], v214 offset:4096
	ds_read_b128 v[158:161], v215
	ds_read_b128 v[204:207], v215 offset:4096
	v_add_f32_e32 v228, v228, v229
	v_cmp_nge_f32_e32 vcc, 0x53800000, v228
	s_cbranch_vccnz .LSPp_redo
	s_add_i32 s86, s86, 1
	s_add_i32 s85, s85, 0x8000
	s_addk_i32 s84, 0x100
	s_add_i32 s83, s83, 64
	s_sub_i32 s82, s82, 64
	v_add_f32_e32 v0, v0, v228
	s_cmpk_eq_u32 s84, 0x8000
	s_cbranch_scc0 .LSPp_top
	s_branch .LSPp_exit

; #define ALAS __attribute__((address_space(3)))
; template <bool WIN> ...
;     ...
;             AT_EXP(s0, 0, p0);
; #pragma unroll
;             for (int kk = 0; kk < 2; ++kk)
; #pragma unroll
;                 for (int db = 0; db < NDB; ++db) vc[kk * NDB + db] = *(const ALAS bf16x8*)(sb + vx[kk + 2] + db * 4096);
;             __builtin_amdgcn_sched_barrier(0);
; #pragma unroll
;             for (int db = 0; db < NDB; ++db) o[db] = __builtin_amdgcn_mfma_f32_32x32x16_bf16(va[db], p0.b, o[db], 0, 0, 0);
;             AT_EXP(s0, 8, p1);
;             __builtin_amdgcn_sched_barrier(0);
; #pragma unroll
;             for (int db = 0; db < NDB; ++db) o[db] = __builtin_amdgcn_mfma_f32_32x32x16_bf16(va[NDB + db], p1.b, o[db], 0, 0, 0);
;             AT_EXP(s1, 0, p2);
;             __builtin_amdgcn_sched_barrier(0);
; #pragma unroll
;             for (int db = 0; db < NDB; ++db) o[db] = __builtin_amdgcn_mfma_f32_32x32x16_bf16(vc[db], p2.b, o[db], 0, 0, 0);
;             AT_EXP(s1, 8, p3);
;             __builtin_amdgcn_sched_barrier(0);
; #pragma unroll
;             for (int db = 0; db < NDB; ++db) o[db] = __builtin_amdgcn_mfma_f32_32x32x16_bf16(vc[NDB + db], p3.b, o[db], 0, 0, 0);
.LSPp_exit:
	s_add_i32 s99, s85, 0xfffe8000
	s_and_b32 s99, s99, 0x18000
	v_add3_u32 v236, s99, v179, v187
	ds_read_b128 v[130:133], v236 offset:16384
	ds_read_b128 v[134:137], v236 offset:20480
	ds_read_b128 v[138:141], v236 offset:24576
	ds_read_b128 v[142:145], v236 offset:28672
	v_add3_u32 v237, s99, v181, v187
	ds_read_b128 v[146:149], v237 offset:16384
	ds_read_b128 v[150:153], v237 offset:20480
	ds_read_b128 v[154:157], v237 offset:24576
	ds_read_b128 v[158:161], v237 offset:28672
	s_waitcnt lgkmcnt(4)
	v_mfma_f32_32x32x16_bf16 v[50:65], v[130:133], v[238:241], v[50:65]
	v_mfma_f32_32x32x16_bf16 v[34:49], v[134:137], v[238:241], v[34:49]
	v_mfma_f32_32x32x16_bf16 v[18:33], v[138:141], v[238:241], v[18:33]
	v_mfma_f32_32x32x16_bf16 v[2:17], v[142:145], v[238:241], v[2:17]
	v_add3_u32 v236, s99, v183, v187
	ds_read_b128 v[130:133], v236 offset:16384
	ds_read_b128 v[134:137], v236 offset:20480
	ds_read_b128 v[138:141], v236 offset:24576
	ds_read_b128 v[142:145], v236 offset:28672
	s_waitcnt lgkmcnt(4)
	v_mfma_f32_32x32x16_bf16 v[50:65], v[146:149], v[242:245], v[50:65]
	v_mfma_f32_32x32x16_bf16 v[34:49], v[150:153], v[242:245], v[34:49]
	v_mfma_f32_32x32x16_bf16 v[18:33], v[154:157], v[242:245], v[18:33]
	v_mfma_f32_32x32x16_bf16 v[2:17], v[158:161], v[242:245], v[2:17]
	v_add3_u32 v237, s99, v190, v187
	ds_read_b128 v[146:149], v237 offset:16384
	ds_read_b128 v[150:153], v237 offset:20480
	ds_read_b128 v[154:157], v237 offset:24576
	ds_read_b128 v[158:161], v237 offset:28672
	s_waitcnt lgkmcnt(4)
	v_mfma_f32_32x32x16_bf16 v[50:65], v[130:133], v[246:249], v[50:65]
	v_mfma_f32_32x32x16_bf16 v[34:49], v[134:137], v[246:249], v[34:49]
	v_mfma_f32_32x32x16_bf16 v[18:33], v[138:141], v[246:249], v[18:33]
	v_mfma_f32_32x32x16_bf16 v[2:17], v[142:145], v[246:249], v[2:17]
	s_waitcnt lgkmcnt(0)
	v_mfma_f32_32x32x16_bf16 v[50:65], v[146:149], v[250:253], v[50:65]
	v_mfma_f32_32x32x16_bf16 v[34:49], v[150:153], v[250:253], v[34:49]
	v_mfma_f32_32x32x16_bf16 v[18:33], v[154:157], v[250:253], v[18:33]
	v_mfma_f32_32x32x16_bf16 v[2:17], v[158:161], v[250:253], v[2:17]
	s_branch .LBB0_262

; #define ALAS __attribute__((address_space(3)))
; template <bool WIN> ...
;     ...
;             if (near) {
;                 const ALAS float* lb = lut + (k0 + 8 * hi - qabs + LUTC);
; #pragma unroll
;                 for (int r = 0; r < 16; ++r) { s0[r] += lb[16 * (r >> 3) + (r & 7)]; s1[r] += lb[32 + 16 * (r >> 3) + (r & 7)];
;                     if ((r & 7) == 7) __builtin_amdgcn_sched_barrier(0); }
;             }
.LSPs_vrd2:
	s_cmp_eq_u32 s64, 0
	s_cbranch_scc1 .LSPs_pv
	v_add_u32_e32 v203, s77, v171
	v_add_u32_e32 v204, 0x23b80, v203
	v_add_u32_e32 v206, 0x23c00, v203
	v_add_u32_e32 v210, 0x23c08, v203
	v_add_u32_e32 v208, 0x23b88, v203
	v_add_u32_e32 v218, 0x23c10, v203
	v_add_u32_e32 v212, 0x23b90, v203
	v_add_u32_e32 v216, 0x23c18, v203
	v_add_u32_e32 v214, 0x23b98, v203
	ds_read2_b32 v[204:205], v204 offset1:1
	ds_read2_b32 v[206:207], v206 offset1:1
	ds_read2_b32 v[208:209], v208 offset1:1
	ds_read2_b32 v[210:211], v210 offset1:1
	ds_read2_b32 v[212:213], v212 offset1:1
	ds_read2_b32 v[214:215], v214 offset1:1
	ds_read2_b32 v[216:217], v216 offset1:1
	ds_read2_b32 v[218:219], v218 offset1:1
	v_add_u32_e32 v220, 0x23bc0, v203
	v_add_u32_e32 v222, 0x23c40, v203
	v_add_u32_e32 v226, 0x23c48, v203
	v_add_u32_e32 v224, 0x23bc8, v203
	v_add_u32_e32 v228, 0x23bd0, v203
	v_add_u32_e32 v234, 0x23c58, v203
	ds_read2_b32 v[220:221], v220 offset1:1
	ds_read2_b32 v[222:223], v222 offset1:1
	ds_read2_b32 v[224:225], v224 offset1:1
	ds_read2_b32 v[226:227], v226 offset1:1
	v_add_u32_e32 v231, 0x23c50, v203
	v_add_u32_e32 v203, 0x23bd8, v203
	ds_read2_b32 v[228:229], v228 offset1:1
	ds_read2_b32 v[232:233], v203 offset1:1
	ds_read2_b32 v[234:235], v234 offset1:1
	ds_read2_b32 v[236:237], v231 offset1:1
	s_waitcnt lgkmcnt(10)
	v_pk_add_f32 v[104:105], v[104:105], v[214:215]
	v_pk_add_f32 v[102:103], v[102:103], v[212:213]
	v_pk_add_f32 v[100:101], v[100:101], v[208:209]
	s_waitcnt lgkmcnt(2)
	v_pk_add_f32 v[112:113], v[112:113], v[232:233]
	v_pk_add_f32 v[110:111], v[110:111], v[228:229]
	v_pk_add_f32 v[108:109], v[108:109], v[224:225]
	v_pk_add_f32 v[106:107], v[106:107], v[220:221]
	v_pk_add_f32 v[98:99], v[98:99], v[204:205]
	v_pk_add_f32 v[88:89], v[88:89], v[216:217]
	v_pk_add_f32 v[86:87], v[86:87], v[218:219]
	v_pk_add_f32 v[84:85], v[84:85], v[210:211]
	s_waitcnt lgkmcnt(1)
	v_pk_add_f32 v[96:97], v[96:97], v[234:235]
	s_waitcnt lgkmcnt(0)
	v_pk_add_f32 v[94:95], v[94:95], v[236:237]
	v_pk_add_f32 v[92:93], v[92:93], v[226:227]
	v_pk_add_f32 v[90:91], v[90:91], v[222:223]
	v_pk_add_f32 v[82:83], v[82:83], v[206:207]
; #define ALAS __attribute__((address_space(3)))
; template <bool WIN> ...
;     ...
;             float ls0 = 0.f, ls1 = 0.f;
;     ...
;             union PFU { u32x4 u; bf16x8 b; };
;             PFU p0, p1, p2, p3;
;             AT_EXP(s0, 0, p0);
; #pragma unroll
;             for (int kk = 0; kk < 2; ++kk)
; #pragma unroll
;                 for (int db = 0; db < NDB; ++db) vc[kk * NDB + db] = *(const ALAS bf16x8*)(sb + vx[kk + 2] + db * 4096);
;             __builtin_amdgcn_sched_barrier(0);
; #pragma unroll
;             for (int db = 0; db < NDB; ++db) o[db] = __builtin_amdgcn_mfma_f32_32x32x16_bf16(va[db], p0.b, o[db], 0, 0, 0);
;             AT_EXP(s0, 8, p1);
;             __builtin_amdgcn_sched_barrier(0);
; #pragma unroll
;             for (int db = 0; db < NDB; ++db) o[db] = __builtin_amdgcn_mfma_f32_32x32x16_bf16(va[NDB + db], p1.b, o[db], 0, 0, 0);
;             AT_EXP(s1, 0, p2);
;             __builtin_amdgcn_sched_barrier(0);
; #pragma unroll
;             for (int db = 0; db < NDB; ++db) o[db] = __builtin_amdgcn_mfma_f32_32x32x16_bf16(vc[db], p2.b, o[db], 0, 0, 0);
;             AT_EXP(s1, 8, p3);
;             __builtin_amdgcn_sched_barrier(0);
; #pragma unroll
;             for (int db = 0; db < NDB; ++db) o[db] = __builtin_amdgcn_mfma_f32_32x32x16_bf16(vc[NDB + db], p3.b, o[db], 0, 0, 0);
;             __builtin_amdgcn_sched_barrier(0);
;     ...
;             l_run += ls0 + ls1;
.LSPs_pv:
	s_cmp_eq_u32 s79, 0
	s_cbranch_scc1 .LSPs_pure
	s_waitcnt lgkmcnt(4)
	v_mfma_f32_32x32x16_bf16 v[50:65], v[130:133], v[238:241], v[50:65]
	v_exp_f32_e32 v98, v98
	v_exp_f32_e32 v99, v99
	v_mfma_f32_32x32x16_bf16 v[34:49], v[134:137], v[238:241], v[34:49]
	v_exp_f32_e32 v100, v100
	v_exp_f32_e32 v101, v101
	v_mfma_f32_32x32x16_bf16 v[18:33], v[138:141], v[238:241], v[18:33]
	v_exp_f32_e32 v102, v102
	v_exp_f32_e32 v103, v103
	v_add_f32_e32 v228, v98, v100
	v_add_f32_e32 v229, v99, v101
	v_mfma_f32_32x32x16_bf16 v[2:17], v[142:145], v[238:241], v[2:17]
	v_exp_f32_e32 v104, v104
	v_exp_f32_e32 v105, v105
	v_add_f32_e32 v228, v228, v102
	v_add_f32_e32 v229, v229, v103
	v_add3_u32 v236, s99, v183, v187
	ds_read_b128 v[130:133], v236 offset:16384
	ds_read_b128 v[134:137], v236 offset:20480
	ds_read_b128 v[138:141], v236 offset:24576
	ds_read_b128 v[142:145], v236 offset:28672
	s_waitcnt lgkmcnt(4)
	v_mfma_f32_32x32x16_bf16 v[50:65], v[146:149], v[242:245], v[50:65]
	v_exp_f32_e32 v106, v106
	v_exp_f32_e32 v107, v107
	v_add_f32_e32 v228, v228, v104
	v_add_f32_e32 v229, v229, v105
	v_cvt_pk_bf16_f32 v238, v98, v99
	v_lshl_add_u64 v[174:175], v[174:175], 0, s[60:61]
	s_add_i32 s80, s78, 0xffff8000
	s_and_b32 s80, s80, 0x18000
	v_mfma_f32_32x32x16_bf16 v[34:49], v[150:153], v[242:245], v[34:49]
	v_exp_f32_e32 v108, v108
	v_exp_f32_e32 v109, v109
	v_add_f32_e32 v228, v228, v106
	v_add_f32_e32 v229, v229, v107
	v_cvt_pk_bf16_f32 v239, v100, v101
	v_lshl_add_u64 v[172:173], v[172:173], 0, s[48:49]
	s_add_i32 s98, s78, 0x10000
	s_and_b32 s98, s98, 0x18000
	v_mfma_f32_32x32x16_bf16 v[18:33], v[154:157], v[242:245], v[18:33]
	v_exp_f32_e32 v110, v110
	v_exp_f32_e32 v111, v111
	v_add_f32_e32 v228, v228, v108
	v_add_f32_e32 v229, v229, v109
	v_cvt_pk_bf16_f32 v240, v102, v103
	v_lshl_add_u64 v[208:209], v[174:175], 0, s[40:41]
	s_add_i32 s98, s98, s29
	s_add_i32 s101, s78, 0x8000
	v_mfma_f32_32x32x16_bf16 v[2:17], v[158:161], v[242:245], v[2:17]
	v_exp_f32_e32 v112, v112
	v_exp_f32_e32 v113, v113
	v_add_f32_e32 v228, v228, v110
	v_add_f32_e32 v229, v229, v111
	v_cvt_pk_bf16_f32 v241, v104, v105
	v_lshl_add_u64 v[210:211], v[172:173], 0, s[40:41]
	s_and_b32 s101, s101, 0x18000
	s_add_i32 s101, s101, s29
	v_add3_u32 v237, s99, v190, v187
	ds_read_b128 v[146:149], v237 offset:16384
	ds_read_b128 v[150:153], v237 offset:20480
	ds_read_b128 v[154:157], v237 offset:24576
	ds_read_b128 v[158:161], v237 offset:28672
	s_waitcnt lgkmcnt(4)
	v_mfma_f32_32x32x16_bf16 v[50:65], v[130:133], v[246:249], v[50:65]
	v_exp_f32_e32 v82, v82
	v_exp_f32_e32 v83, v83
	v_add_f32_e32 v228, v228, v112
	v_add_f32_e32 v229, v229, v113
	v_cvt_pk_bf16_f32 v242, v106, v107
	v_add3_u32 v212, s80, v178, v162
	s_add_i32 s99, s76, 64
	s_cmp_gt_u32 s99, s28
	v_mfma_f32_32x32x16_bf16 v[34:49], v[134:137], v[246:249], v[34:49]
	v_exp_f32_e32 v84, v84
	v_exp_f32_e32 v85, v85
	v_add_f32_e32 v228, v228, v82
	v_add_f32_e32 v229, v229, v83
	v_cvt_pk_bf16_f32 v243, v108, v109
	v_add3_u32 v213, s80, v180, v162
	s_cselect_b32 m0, s31, s30
	s_cmp_lt_u32 s99, s33
	v_mfma_f32_32x32x16_bf16 v[18:33], v[138:141], v[246:249], v[18:33]
	v_exp_f32_e32 v86, v86
	v_exp_f32_e32 v87, v87
	v_add_f32_e32 v228, v228, v84
	v_add_f32_e32 v229, v229, v85
	v_cvt_pk_bf16_f32 v244, v110, v111
	v_add3_u32 v214, s80, v182, v162
	s_cselect_b32 s65, 1, 0
	s_cmp_gt_i32 s99, s67
	v_mfma_f32_32x32x16_bf16 v[2:17], v[142:145], v[246:249], v[2:17]
	v_exp_f32_e32 v88, v88
	v_exp_f32_e32 v89, v89
	v_add_f32_e32 v228, v228, v86
	v_add_f32_e32 v229, v229, v87
	v_cvt_pk_bf16_f32 v245, v112, v113
	v_add3_u32 v215, s80, v184, v162
	s_cselect_b32 s65, s65, 0
	s_cmp_lg_u32 s65, 0
	s_waitcnt lgkmcnt(0)
	v_mfma_f32_32x32x16_bf16 v[50:65], v[146:149], v[250:253], v[50:65]
	v_exp_f32_e32 v90, v90
	v_exp_f32_e32 v91, v91
	v_add_f32_e32 v228, v228, v88
	v_add_f32_e32 v229, v229, v89
	v_cvt_pk_bf16_f32 v246, v82, v83
	s_cselect_b32 m0, 0, m0
	s_add_i32 s99, s78, 0xffff0000
	v_mfma_f32_32x32x16_bf16 v[34:49], v[150:153], v[250:253], v[34:49]
	v_exp_f32_e32 v92, v92
	v_exp_f32_e32 v93, v93
	v_add_f32_e32 v228, v228, v90
	v_add_f32_e32 v229, v229, v91
	v_cvt_pk_bf16_f32 v247, v84, v85
	s_and_b32 s99, s99, 0x18000
	v_mfma_f32_32x32x16_bf16 v[18:33], v[154:157], v[250:253], v[18:33]
	v_exp_f32_e32 v94, v94
	v_exp_f32_e32 v95, v95
	v_add_f32_e32 v228, v228, v92
	v_add_f32_e32 v229, v229, v93
	v_cvt_pk_bf16_f32 v248, v86, v87
	v_mfma_f32_32x32x16_bf16 v[2:17], v[158:161], v[250:253], v[2:17]
	v_exp_f32_e32 v96, v96
	v_exp_f32_e32 v97, v97
	v_add_f32_e32 v228, v228, v94
	v_add_f32_e32 v229, v229, v95
	v_cvt_pk_bf16_f32 v249, v88, v89
	v_add_f32_e32 v228, v228, v96
	v_add_f32_e32 v229, v229, v97
	v_cvt_pk_bf16_f32 v250, v90, v91
	v_cvt_pk_bf16_f32 v251, v92, v93
	v_cvt_pk_bf16_f32 v252, v94, v95
	v_cvt_pk_bf16_f32 v253, v96, v97
	ds_read_b128 v[130:133], v212
	ds_read_b128 v[134:137], v212 offset:4096
	ds_read_b128 v[138:141], v213
	ds_read_b128 v[142:145], v213 offset:4096
	ds_read_b128 v[146:149], v214
	ds_read_b128 v[150:153], v214 offset:4096
	ds_read_b128 v[158:161], v215
	ds_read_b128 v[204:207], v215 offset:4096
	v_add_f32_e32 v228, v228, v229
	v_cmp_nge_f32_e32 vcc, 0x53800000, v228
	s_cbranch_vccnz .LSPs_redo
	s_add_i32 s79, s79, 1
	s_add_i32 s78, s78, 0x8000
	s_addk_i32 s77, 0x100
	s_add_i32 s76, s76, 64
	v_add_f32_e32 v0, v0, v228
	s_cmpk_eq_i32 s77, 0x2000
	s_cbranch_scc0 .LSPs_top
	s_branch .LSPs_exit

; #define ALAS __attribute__((address_space(3)))
; template <bool WIN> ...
;     ...
;             AT_EXP(s0, 0, p0);
; #pragma unroll
;             for (int kk = 0; kk < 2; ++kk)
; #pragma unroll
;                 for (int db = 0; db < NDB; ++db) vc[kk * NDB + db] = *(const ALAS bf16x8*)(sb + vx[kk + 2] + db * 4096);
;             __builtin_amdgcn_sched_barrier(0);
; #pragma unroll
;             for (int db = 0; db < NDB; ++db) o[db] = __builtin_amdgcn_mfma_f32_32x32x16_bf16(va[db], p0.b, o[db], 0, 0, 0);
;             AT_EXP(s0, 8, p1);
;             __builtin_amdgcn_sched_barrier(0);
; #pragma unroll
;             for (int db = 0; db < NDB; ++db) o[db] = __builtin_amdgcn_mfma_f32_32x32x16_bf16(va[NDB + db], p1.b, o[db], 0, 0, 0);
;             AT_EXP(s1, 0, p2);
;             __builtin_amdgcn_sched_barrier(0);
; #pragma unroll
;             for (int db = 0; db < NDB; ++db) o[db] = __builtin_amdgcn_mfma_f32_32x32x16_bf16(vc[db], p2.b, o[db], 0, 0, 0);
;             AT_EXP(s1, 8, p3);
;             __builtin_amdgcn_sched_barrier(0);
; #pragma unroll
;             for (int db = 0; db < NDB; ++db) o[db] = __builtin_amdgcn_mfma_f32_32x32x16_bf16(vc[NDB + db], p3.b, o[db], 0, 0, 0);
.LSPs_exit:
	s_add_i32 s99, s78, 0xfffe8000
	s_and_b32 s99, s99, 0x18000
	v_add3_u32 v236, s99, v179, v187
	ds_read_b128 v[130:133], v236 offset:16384
	ds_read_b128 v[134:137], v236 offset:20480
	ds_read_b128 v[138:141], v236 offset:24576
	ds_read_b128 v[142:145], v236 offset:28672
	v_add3_u32 v237, s99, v181, v187
	ds_read_b128 v[146:149], v237 offset:16384
	ds_read_b128 v[150:153], v237 offset:20480
	ds_read_b128 v[154:157], v237 offset:24576
	ds_read_b128 v[158:161], v237 offset:28672
	s_waitcnt lgkmcnt(4)
	v_mfma_f32_32x32x16_bf16 v[50:65], v[130:133], v[238:241], v[50:65]
	v_mfma_f32_32x32x16_bf16 v[34:49], v[134:137], v[238:241], v[34:49]
	v_mfma_f32_32x32x16_bf16 v[18:33], v[138:141], v[238:241], v[18:33]
	v_mfma_f32_32x32x16_bf16 v[2:17], v[142:145], v[238:241], v[2:17]
	v_add3_u32 v236, s99, v183, v187
	ds_read_b128 v[130:133], v236 offset:16384
	ds_read_b128 v[134:137], v236 offset:20480
	ds_read_b128 v[138:141], v236 offset:24576
	ds_read_b128 v[142:145], v236 offset:28672
	s_waitcnt lgkmcnt(4)
	v_mfma_f32_32x32x16_bf16 v[50:65], v[146:149], v[242:245], v[50:65]
	v_mfma_f32_32x32x16_bf16 v[34:49], v[150:153], v[242:245], v[34:49]
	v_mfma_f32_32x32x16_bf16 v[18:33], v[154:157], v[242:245], v[18:33]
	v_mfma_f32_32x32x16_bf16 v[2:17], v[158:161], v[242:245], v[2:17]
	v_add3_u32 v237, s99, v190, v187
	ds_read_b128 v[146:149], v237 offset:16384
	ds_read_b128 v[150:153], v237 offset:20480
	ds_read_b128 v[154:157], v237 offset:24576
	ds_read_b128 v[158:161], v237 offset:28672
	s_waitcnt lgkmcnt(4)
	v_mfma_f32_32x32x16_bf16 v[50:65], v[130:133], v[246:249], v[50:65]
	v_mfma_f32_32x32x16_bf16 v[34:49], v[134:137], v[246:249], v[34:49]
	v_mfma_f32_32x32x16_bf16 v[18:33], v[138:141], v[246:249], v[18:33]
	v_mfma_f32_32x32x16_bf16 v[2:17], v[142:145], v[246:249], v[2:17]
	s_waitcnt lgkmcnt(0)
	v_mfma_f32_32x32x16_bf16 v[50:65], v[146:149], v[250:253], v[50:65]
	v_mfma_f32_32x32x16_bf16 v[34:49], v[150:153], v[250:253], v[34:49]
	v_mfma_f32_32x32x16_bf16 v[18:33], v[154:157], v[250:253], v[18:33]
	v_mfma_f32_32x32x16_bf16 v[2:17], v[158:161], v[250:253], v[2:17]
	s_branch .LBB0_286
